# S5 sample item: all loads of the item issued in the first batch (gate value of token 0, last u quad, skip value prefetched)
# baseline (speedup 1.0000x reference)
; __device__ __forceinline__ float bf1(bf16 h) { return __uint_as_float((unsigned)h << 16); }
; __device__ __forceinline__ void s5_sample_wave(int lane, int b, int g, const float* tb, const float* cre, const float* cim, const float* dsk,
;                                                const bf16* US, bf16* YS, const float* st_re, const float* st_im, float* out_re, float* out_im) {
;     const int p = lane, gp = g * 64 + p;
;     const float ar = tb[gp], ai = tb[2048 + gp];
;     float bbr[16], bbi[16], cr[16], ci[16];
; #pragma unroll
;     for (int q = 0; q < 4; ++q) { const f32x4 a = *(const f32x4*)(tb + 4096 + gp * 16 + 4 * q), c = *(const f32x4*)(tb + 4096 + 32768 + gp * 16 + 4 * q);
; #pragma unroll
;         for (int j = 0; j < 4; ++j) { bbr[4 * q + j] = a[j]; bbi[4 * q + j] = c[j]; } }
; #pragma unroll
;     for (int h = 0; h < 16; ++h) { cr[h] = cre[(size_t)(g * 16 + h) * 64 + p]; ci[h] = cim[(size_t)(g * 16 + h) * 64 + p]; }
;     float hr = st_re[(size_t)(b * NG + g) * NP + p], hi = st_im[(size_t)(b * NG + g) * NP + p];
;     const int ho = ((lane >> 5) & 1) * 8 + ((lane >> 4) & 1) * 4 + ((lane >> 3) & 1) * 2 + ((lane >> 2) & 1);
;     const bf16* up0 = US + ((size_t)g * M + MP + (size_t)b * DECS) * 16;
;     v4u qa[DECS], qb[DECS]; float uho[DECS];
; #pragma unroll
;     for (int j = 0; j < DECS; ++j) { qa[j] = *(const v4u*)(up0 + 16 * j); qb[j] = *(const v4u*)(up0 + 16 * j + 8); uho[j] = bf1(up0[16 * j + ho]); }
;     const float dkh = dsk[g * 16 + ho];
.LBB0_893:
	s_ashr_i32 s12, s2, 5
	v_readlane_b32 s36, v252, 10
	v_readlane_b32 s24, v252, 4
	s_and_b32 s58, s2, 31
	v_readlane_b32 s42, v252, 16
	v_readlane_b32 s43, v252, 17
	v_readlane_b32 s25, v252, 5
	s_ashr_i32 s13, s12, 31
	s_mov_b64 s[34:35], s[42:43]
	s_mov_b64 s[30:31], s[24:25]
	s_mov_b64 s[28:29], s[24:25]
	s_lshl_b32 s42, s58, 6
	s_lshl_b64 s[24:25], s[12:13], 7
	s_add_u32 s3, s74, s24
	s_addc_u32 s13, s75, s25
	s_mul_i32 s24, s58, 0x84000
	s_add_u32 s24, s3, s24
	v_readlane_b32 s40, v252, 14
	v_readlane_b32 s41, v252, 15
	s_addc_u32 s25, s13, 0
	s_mov_b64 s[14:15], s[40:41]
	s_add_u32 s40, s24, 0x80000
	v_readlane_b32 s26, v252, 6
	s_addc_u32 s41, s25, 0
	v_readlane_b32 s27, v252, 7
	s_add_u32 s26, s24, 0x80040
	v_or_b32_e32 v4, s42, v196
	s_addc_u32 s27, s25, 0
	v_lshlrev_b32_e32 v2, 2, v4
	global_load_dwordx4 v[40:43], v246, s[24:25] offset:64
	global_load_dwordx4 v[90:93], v3, s[26:27] offset:48
	global_load_dwordx4 v[94:97], v3, s[26:27] offset:32
	global_load_dwordx4 v[98:101], v3, s[26:27] offset:16
	v_lshl_or_b32 v36, s58, 12, v48
	global_load_dwordx4 v[102:105], v246, s[24:25]
	global_load_dword v67, v36, s[18:19]
	global_load_dword v63, v36, s[18:19] offset:256
	global_load_dword v60, v36, s[18:19] offset:512
	global_load_dword v56, v36, s[18:19] offset:768
	global_load_dword v55, v36, s[18:19] offset:1024
	global_load_dword v54, v36, s[18:19] offset:1280
	global_load_dword v49, v36, s[18:19] offset:1536
	global_load_dword v45, v36, s[18:19] offset:1792
	v_lshlrev_b32_e32 v24, 6, v4
	global_load_dword v74, v2, s[72:73]
	global_load_dwordx4 v[106:109], v3, s[40:41] offset:16
	global_load_dwordx4 v[4:7], v24, s[68:69] offset:48
	global_load_dwordx4 v[28:31], v24, s[70:71]
	v_lshl_add_u64 v[8:9], s[72:73], 0, v[2:3]
	v_add_co_u32_e32 v8, vcc, s33, v8
	v_lshl_add_u64 v[38:39], s[34:35], 0, v[50:51]
	s_nop 0
	v_addc_co_u32_e32 v9, vcc, 0, v9, vcc
	global_load_dword v77, v[8:9], off
	global_load_dwordx4 v[32:35], v24, s[68:69]
	s_nop 0
	global_load_dwordx4 v[8:11], v24, s[68:69] offset:32
	global_load_dwordx4 v[16:19], v24, s[68:69] offset:16
	global_load_dwordx4 v[12:15], v24, s[70:71] offset:32
	global_load_dwordx4 v[20:23], v24, s[70:71] offset:16
	global_load_dword v83, v36, s[20:21]
	global_load_dword v80, v36, s[20:21] offset:256
	global_load_dword v76, v36, s[20:21] offset:512
	global_load_dword v72, v36, s[20:21] offset:768
	global_load_dword v69, v36, s[20:21] offset:1024
	global_load_dword v65, v36, s[20:21] offset:1280
	global_load_dword v62, v36, s[20:21] offset:1536
	global_load_dword v57, v36, s[20:21] offset:1792
	global_load_dword v85, v36, s[18:19] offset:2048
	global_load_dword v82, v36, s[18:19] offset:2304
	global_load_dword v79, v36, s[18:19] offset:2560
	global_load_dword v75, v36, s[18:19] offset:2816
	global_load_dword v71, v36, s[18:19] offset:3072
	global_load_dword v68, v36, s[18:19] offset:3328
	global_load_dword v64, v36, s[18:19] offset:3584
	global_load_dword v61, v36, s[18:19] offset:3840
	s_nop 0
	global_load_dwordx4 v[24:27], v24, s[70:71] offset:48
	s_nop 0
	global_load_dword v87, v36, s[20:21] offset:2048
	global_load_dword v86, v36, s[20:21] offset:2304
	global_load_dword v84, v36, s[20:21] offset:2560
	global_load_dword v81, v36, s[20:21] offset:2816
	global_load_dword v78, v36, s[20:21] offset:3072
	global_load_dword v73, v36, s[20:21] offset:3328
	global_load_dword v70, v36, s[20:21] offset:3584
	global_load_dword v66, v36, s[20:21] offset:3840
	v_lshl_add_u64 v[36:37], s[14:15], 0, v[50:51]
	global_load_dword v110, v[38:39], off
	global_load_dword v111, v[36:37], off
	v_readlane_b32 s45, v252, 19
	v_readlane_b32 s46, v252, 20
	v_readlane_b32 s49, v252, 23
	v_readlane_b32 s51, v252, 25
	v_readlane_b32 s44, v252, 18
	v_readlane_b32 s47, v252, 21
	v_readlane_b32 s48, v252, 22
	v_readlane_b32 s50, v252, 24
	v_lshlrev_b32_e32 v2, 1, v44
	global_load_dwordx4 v[36:39], v3, s[40:41] offset:32
	global_load_ushort v89, v2, s[40:41] offset:32
	v_lshl_or_b32 v52, v44, 2, s42
	global_load_ushort v112, v2, s[40:41]
	global_load_dwordx4 v[116:119], v3, s[40:41] offset:48
	global_load_ushort v88, v2, s[40:41] offset:64
	global_load_ushort v59, v2, s[40:41] offset:96
	global_load_dword v58, v52, s[52:53]
	s_lshl_b32 s34, s12, 2
	s_lshl_b32 s84, s58, 5
	s_ashr_i32 s35, s34, 31
	v_readlane_b32 s37, v252, 11
	v_readlane_b32 s38, v252, 12
	v_readlane_b32 s39, v252, 13
	s_waitcnt vmcnt(0)
; __device__ __forceinline__ float bflo(unsigned w) { return __uint_as_float(w << 16); }
; __device__ __forceinline__ float bfhi(unsigned w) { return __uint_as_float(w & 0xffff0000u); }
; __device__ __forceinline__ void s5_sample_wave(int lane, int b, int g, const float* tb, const float* cre, const float* cim, const float* dsk,
;                                                const bf16* US, bf16* YS, const float* st_re, const float* st_im, float* out_re, float* out_im) {
;     ...
;         u[0] = bflo(q0.x); u[1] = bfhi(q0.x); u[2] = bflo(q0.y); u[3] = bfhi(q0.y); u[4] = bflo(q0.z); u[5] = bfhi(q0.z); u[6] = bflo(q0.w); u[7] = bfhi(q0.w);
;         u[8] = bflo(q1.x); u[9] = bfhi(q1.x); u[10] = bflo(q1.y); u[11] = bfhi(q1.y); u[12] = bflo(q1.z); u[13] = bfhi(q1.z); u[14] = bflo(q1.w); u[15] = bfhi(q1.w);
;         float br = 0.f, bi = 0.f;
; #pragma unroll
;         for (int h = 0; h < 16; ++h) { br += bbr[h] * u[h]; bi += bbi[h] * u[h]; }
;         const float nr = ar * hr - ai * hi + br, ni = ar * hi + ai * hr + bi; hr = nr; hi = ni;
;         float v8[8], v4[4], v2[2], v1;
; #pragma unroll
;         for (int h = 0; h < 8; ++h) { const float lo = cr[h] * hr - ci[h] * hi, hi8 = cr[h + 8] * hr - ci[h + 8] * hi; const bool up5 = (lane & 32) != 0;
;             const float keep = up5 ? hi8 : lo, send = up5 ? lo : hi8; v8[h] = keep + fshx<32>(send); }
; #pragma unroll
;         for (int h = 0; h < 4; ++h) { const bool b = (lane & 16) != 0; const float keep = b ? v8[h + 4] : v8[h], send = b ? v8[h] : v8[h + 4]; v4[h] = keep + fshx<16>(send); }
; #pragma unroll
;         for (int h = 0; h < 2; ++h) { const bool b = (lane & 8) != 0; const float keep = b ? v4[h + 2] : v4[h], send = b ? v4[h] : v4[h + 2]; v2[h] = keep + fshx<8>(send); }
;         { const bool b = (lane & 4) != 0; const float keep = b ? v2[1] : v2[0], send = b ? v2[0] : v2[1]; v1 = keep + fshx<4>(send); }
;         v1 += fshx<2>(v1); v1 += fshx<1>(v1);
	v_readfirstlane_b32 s26, v90
	v_lshlrev_b32_e32 v90, 16, v102
	v_readfirstlane_b32 s25, v91
	v_readfirstlane_b32 s45, v95
	v_readfirstlane_b32 s46, v94
	v_readfirstlane_b32 s49, v101
	v_readfirstlane_b32 s51, v100
	v_and_b32_e32 v91, 0xffff0000, v102
	v_lshlrev_b32_e32 v94, 16, v103
	v_and_b32_e32 v95, 0xffff0000, v103
	v_lshlrev_b32_e32 v100, 16, v106
	v_and_b32_e32 v101, 0xffff0000, v106
	v_lshlrev_b32_e32 v102, 16, v107
	v_and_b32_e32 v103, 0xffff0000, v107
	v_lshlrev_b32_e32 v106, 16, v109
	v_and_b32_e32 v107, 0xffff0000, v109
	v_fma_f32 v109, v28, v90, 0
	v_readfirstlane_b32 s27, v97
	v_readfirstlane_b32 s44, v96
	v_readfirstlane_b32 s55, v99
	v_readfirstlane_b32 s57, v98
	v_lshlrev_b32_e32 v96, 16, v104
	v_and_b32_e32 v97, 0xffff0000, v104
	v_lshlrev_b32_e32 v98, 16, v105
	v_and_b32_e32 v99, 0xffff0000, v105
	v_lshlrev_b32_e32 v104, 16, v108
	v_and_b32_e32 v105, 0xffff0000, v108
	v_fma_f32 v108, v32, v90, 0
	v_fmac_f32_e32 v109, v29, v91
	v_fmac_f32_e32 v108, v33, v91
	v_fmac_f32_e32 v109, v30, v94
	v_fmac_f32_e32 v108, v34, v94
	v_fmac_f32_e32 v109, v31, v95
	v_readfirstlane_b32 s47, v43
	v_readfirstlane_b32 s48, v42
	v_readfirstlane_b32 s50, v41
	v_readfirstlane_b32 s54, v40
	v_mov_b64_e32 v[40:41], v[116:117]
	v_mov_b64_e32 v[42:43], v[118:119]
	v_fmac_f32_e32 v108, v35, v95
	v_fmac_f32_e32 v109, v20, v96
	v_fmac_f32_e32 v108, v16, v96
	v_fmac_f32_e32 v109, v21, v97
	v_fmac_f32_e32 v108, v17, v97
	v_fmac_f32_e32 v109, v22, v98
	v_fmac_f32_e32 v108, v18, v98
	v_fmac_f32_e32 v109, v23, v99
	v_fmac_f32_e32 v108, v19, v99
	v_fmac_f32_e32 v109, v12, v100
	v_fmac_f32_e32 v108, v8, v100
	v_fmac_f32_e32 v109, v13, v101
	v_fmac_f32_e32 v108, v9, v101
	v_fmac_f32_e32 v109, v14, v102
	v_fmac_f32_e32 v108, v10, v102
	v_fmac_f32_e32 v109, v15, v103
	v_fmac_f32_e32 v108, v11, v103
	v_fmac_f32_e32 v109, v24, v104
	v_fmac_f32_e32 v108, v4, v104
	v_fmac_f32_e32 v109, v25, v105
	v_fmac_f32_e32 v108, v5, v105
	v_fmac_f32_e32 v109, v26, v106
	v_mul_f32_e32 v91, v74, v110
	v_fmac_f32_e32 v108, v6, v106
	v_fmac_f32_e32 v109, v27, v107
	v_mul_f32_e32 v90, v77, v110
	v_fmac_f32_e32 v91, v77, v111
	v_fmac_f32_e32 v108, v7, v107
	v_fma_f32 v90, v74, v111, -v90
	v_add_f32_e32 v91, v91, v109
	v_add_f32_e32 v90, v90, v108
	v_mul_f32_e32 v94, v83, v91
	v_mul_f32_e32 v95, v87, v91
	v_fma_f32 v94, v67, v90, -v94
	v_fma_f32 v95, v85, v90, -v95
	v_cndmask_b32_e64 v96, v95, v94, s[0:1]
	v_cndmask_b32_e64 v94, v94, v95, s[0:1]
	v_readfirstlane_b32 s24, v92
	v_and_b32_e32 v92, 32, v247
	v_mov_b32_e32 v95, v94
	s_nop 1
	v_permlane32_swap_b32_e32 v94, v95
	v_cmp_eq_u32_e64 s[12:13], 0, v92
	v_readfirstlane_b32 s3, v93
	v_and_b32_e32 v93, 16, v247
	v_cndmask_b32_e64 v92, v94, v95, s[12:13]
	v_mul_f32_e32 v94, v80, v91
	v_mul_f32_e32 v95, v86, v91
	v_fma_f32 v94, v63, v90, -v94
	v_fma_f32 v95, v82, v90, -v95
	v_add_f32_e32 v92, v96, v92
	v_cndmask_b32_e64 v96, v95, v94, s[0:1]
	v_cndmask_b32_e64 v94, v94, v95, s[0:1]
	v_mov_b32_e32 v95, v94
	s_nop 1
	v_permlane32_swap_b32_e32 v94, v95
	v_cndmask_b32_e64 v94, v94, v95, s[12:13]
	v_add_f32_e32 v94, v96, v94
	v_mul_f32_e32 v95, v76, v91
	v_mul_f32_e32 v96, v84, v91
	v_fma_f32 v95, v60, v90, -v95
	v_fma_f32 v96, v79, v90, -v96
	v_cndmask_b32_e64 v97, v96, v95, s[0:1]
	v_cndmask_b32_e64 v95, v95, v96, s[0:1]
	v_mov_b32_e32 v96, v95
	s_nop 1
	v_permlane32_swap_b32_e32 v95, v96
	v_cndmask_b32_e64 v95, v95, v96, s[12:13]
	v_add_f32_e32 v95, v97, v95
	v_mul_f32_e32 v96, v72, v91
	v_mul_f32_e32 v97, v81, v91
	v_fma_f32 v96, v56, v90, -v96
	v_fma_f32 v97, v75, v90, -v97
	v_cndmask_b32_e64 v98, v97, v96, s[0:1]
	v_cndmask_b32_e64 v96, v96, v97, s[0:1]
	v_mov_b32_e32 v97, v96
	s_nop 1
	v_permlane32_swap_b32_e32 v96, v97
	v_cndmask_b32_e64 v96, v96, v97, s[12:13]
	v_add_f32_e32 v96, v98, v96
	v_mul_f32_e32 v97, v69, v91
	v_mul_f32_e32 v98, v78, v91
	v_fma_f32 v97, v55, v90, -v97
	v_fma_f32 v98, v71, v90, -v98
	v_cndmask_b32_e64 v99, v98, v97, s[0:1]
	v_cndmask_b32_e64 v97, v97, v98, s[0:1]
	v_mov_b32_e32 v98, v97
	s_nop 1
	v_permlane32_swap_b32_e32 v97, v98
	v_cndmask_b32_e64 v97, v97, v98, s[12:13]
	v_add_f32_e32 v97, v99, v97
	v_mul_f32_e32 v98, v65, v91
	v_mul_f32_e32 v99, v73, v91
	v_fma_f32 v98, v54, v90, -v98
	v_fma_f32 v99, v68, v90, -v99
	v_cndmask_b32_e64 v100, v99, v98, s[0:1]
	v_cndmask_b32_e64 v98, v98, v99, s[0:1]
	v_mov_b32_e32 v99, v98
	s_nop 1
	v_permlane32_swap_b32_e32 v98, v99
	v_cndmask_b32_e64 v98, v98, v99, s[12:13]
	v_add_f32_e32 v98, v100, v98
	v_mul_f32_e32 v99, v62, v91
	v_mul_f32_e32 v100, v70, v91
	v_fma_f32 v99, v49, v90, -v99
	v_fma_f32 v100, v64, v90, -v100
	v_cndmask_b32_e64 v101, v100, v99, s[0:1]
	v_cndmask_b32_e64 v99, v99, v100, s[0:1]
	v_mov_b32_e32 v100, v99
	s_nop 1
	v_permlane32_swap_b32_e32 v99, v100
	v_cndmask_b32_e64 v99, v99, v100, s[12:13]
	v_add_f32_e32 v99, v101, v99
	v_mul_f32_e32 v100, v57, v91
	v_mul_f32_e32 v101, v66, v91
	v_fma_f32 v100, v45, v90, -v100
	v_fma_f32 v101, v61, v90, -v101
	v_cndmask_b32_e64 v102, v101, v100, s[0:1]
	v_cndmask_b32_e64 v100, v100, v101, s[0:1]
	v_mov_b32_e32 v101, v100
	s_nop 1
	v_permlane32_swap_b32_e32 v100, v101
	v_cndmask_b32_e64 v100, v100, v101, s[12:13]
	v_cndmask_b32_e64 v101, v97, v92, s[4:5]
	v_cndmask_b32_e64 v92, v92, v97, s[4:5]
	v_mov_b32_e32 v97, v92
	s_nop 1
	v_permlane16_swap_b32_e32 v92, v97
	v_cmp_eq_u32_e64 s[14:15], 0, v93
	v_cndmask_b32_e64 v93, v98, v94, s[4:5]
	v_cndmask_b32_e64 v94, v94, v98, s[4:5]
	v_cndmask_b32_e64 v92, v92, v97, s[14:15]
	v_mov_b32_e32 v97, v94
	s_nop 1
	v_permlane16_swap_b32_e32 v94, v97
	v_cndmask_b32_e64 v94, v94, v97, s[14:15]
	v_add_f32_e32 v93, v93, v94
	v_cndmask_b32_e64 v94, v99, v95, s[4:5]
	v_cndmask_b32_e64 v95, v95, v99, s[4:5]
	v_mov_b32_e32 v97, v95
	s_nop 1
	v_permlane16_swap_b32_e32 v95, v97
	v_add_f32_e32 v100, v102, v100
	v_cndmask_b32_e64 v95, v95, v97, s[14:15]
	v_add_f32_e32 v94, v94, v95
	v_cndmask_b32_e64 v95, v100, v96, s[4:5]
	v_cndmask_b32_e64 v96, v96, v100, s[4:5]
	v_mov_b32_e32 v97, v96
	s_nop 1
	v_permlane16_swap_b32_e32 v96, v97
	v_cndmask_b32_e64 v96, v96, v97, s[14:15]
	v_add_f32_e32 v92, v101, v92
	v_add_f32_e32 v95, v95, v96
	v_cndmask_b32_e64 v96, v94, v92, s[6:7]
	v_cndmask_b32_e64 v92, v92, v94, s[6:7]
	v_cndmask_b32_e64 v94, v95, v93, s[6:7]
	v_cndmask_b32_e64 v93, v93, v95, s[6:7]
	v_add_f32_dpp v92, v92, v96 row_ror:8 row_mask:0xf bank_mask:0xf bound_ctrl:1
	v_lshl_add_u64 v[52:53], v[46:47], 0, s[84:85]
	v_add_f32_dpp v93, v93, v94 row_ror:8 row_mask:0xf bank_mask:0xf bound_ctrl:1
	v_cndmask_b32_e64 v94, v93, v92, s[8:9]
	v_cndmask_b32_e64 v92, v92, v93, s[8:9]
	s_nop 1
	v_mov_b32_dpp v92, v92 row_half_mirror row_mask:0xf bank_mask:0xf bound_ctrl:1
	s_nop 1
	v_add_f32_dpp v92, v92, v94 quad_perm:[3,2,1,0] row_mask:0xf bank_mask:0xf bound_ctrl:1
	s_nop 1
	v_add_f32_dpp v92, v92, v92 quad_perm:[2,3,0,1] row_mask:0xf bank_mask:0xf bound_ctrl:1
	s_nop 1
	v_mov_b32_dpp v93, v92 quad_perm:[1,0,3,2] row_mask:0xf bank_mask:0xf bound_ctrl:1
	s_and_saveexec_b64 s[42:43], s[10:11]
	s_cbranch_execz .LBB0_895
; __device__ __forceinline__ float gelu_tanh(float x) { const float u = 1.5957691216057308f * (x + 0.044715f * x * x * x); return x * sigmoid_f(u); }
; __device__ __forceinline__ unsigned f2bf(float f) { unsigned u = __builtin_bit_cast(unsigned, f); return (u + 0x7fffu + ((u >> 16) & 1u)) >> 16; }
; __device__ __forceinline__ void s5_sample_wave(int lane, int b, int g, const float* tb, const float* cre, const float* cim, const float* dsk,
;                                                const bf16* US, bf16* YS, const float* st_re, const float* st_im, float* out_re, float* out_im) {
;     ...
;         const float yv = v1 + dkh * uho[j];
;         if ((lane & 3) == 0) YS[row * SSMW + g * 16 + ho] = (bf16)f2bf(gelu_tanh(yv));
	v_lshl_add_u64 v[94:95], s[40:41], 0, v[2:3]
	v_add_f32_e32 v94, v92, v93
	s_lshl_b64 s[40:41], s[34:35], 10
	v_lshl_add_u64 v[92:93], v[52:53], 0, s[40:41]
	v_add_co_u32_e32 v92, vcc, 0x1000000, v92
	s_movk_i32 s36, 0x7fff
	s_nop 0
	v_addc_co_u32_e32 v93, vcc, 0, v93, vcc
	v_lshlrev_b32_e32 v2, 16, v112
	v_fmac_f32_e32 v94, v58, v2
	v_mul_f32_e32 v2, 0x3d372713, v94
	v_mul_f32_e32 v2, v94, v2
	v_fma_f32 v2, v94, v2, v94
	v_mul_f32_e32 v2, 0x3fcc422a, v2
	v_mul_f32_e32 v2, 0xbfb8aa3b, v2
	v_exp_f32_e32 v2, v2
	s_nop 0
	v_add_f32_e32 v2, 1.0, v2
	v_rcp_f32_e32 v2, v2
	s_nop 0
	v_mul_f32_e32 v2, v94, v2
	v_bfe_u32 v94, v2, 16, 1
	v_add3_u32 v2, v2, v94, s36
	global_store_short_d16_hi v[92:93], v2, off
